# attention item table: slot s of every workgroup takes an item of head pair (2s, 2s+1), costs balanced across workgroups, so an XCD streams two heads' K/V at a time
# baseline (speedup 1.0000x reference)
.Ltbl:
	s_and_b32 s0, s73, 15
	s_mov_b32 s100, 0x40785ee9
	s_cmp_eq_u32 s0, 1
	s_cselect_b32 s100, 0x4059dad8, s100
	s_cmp_eq_u32 s0, 2
	s_cselect_b32 s100, 0x403bc4d1, s100
	s_cmp_eq_u32 s0, 3
	s_cselect_b32 s100, 0x405ed6d9, s100
	s_cmp_eq_u32 s0, 4
	s_cselect_b32 s100, 0x40f94480, s100
	s_cmp_eq_u32 s0, 5
	s_cselect_b32 s100, 0x40dd52b8, s100
	s_cmp_eq_u32 s0, 6
	s_cselect_b32 s100, 0x409a4a81, s100
	s_cmp_eq_u32 s0, 7
	s_cselect_b32 s100, 0x40bc4cb9, s100
	s_cmp_eq_u32 s0, 8
	s_cselect_b32 s100, 0x40b9c690, s100
	s_cmp_eq_u32 s0, 9
	s_cselect_b32 s100, 0x401f58a1, s100
	s_cmp_eq_u32 s0, 10
	s_cselect_b32 s100, 0x409cdcc9, s100
	s_cmp_eq_u32 s0, 11
	s_cselect_b32 s100, 0x407fd0e0, s100
	s_cmp_eq_u32 s0, 12
	s_cselect_b32 s100, 0x40dac088, s100
	s_cmp_eq_u32 s0, 13
	s_cselect_b32 s100, 0x403e58f1, s100
	s_cmp_eq_u32 s0, 14
	s_cselect_b32 s100, 0x40fcc2f0, s100
	s_cmp_eq_u32 s0, 15
	s_cselect_b32 s100, 0x401b4ea8, s100
	s_mov_b32 s74, 0
